# Toeplitz-image loop (phase 2): up to four item loads in flight before the first convert/store
# baseline (speedup 1.0000x reference)
; __device__ __forceinline__ unsigned pk2(float lo, float hi) { typedef float f2v __attribute__((ext_vector_type(2))); typedef __bf16 b2v __attribute__((ext_vector_type(2))); const f2v v = {lo, hi}; const b2v b = __builtin_convertvector(v, b2v); return __builtin_bit_cast(unsigned, b); }
; #define lane lane_id()
; __device__ __forceinline__ void s5_toeplitz_item(const Prm& P, int item, int lane) {
;     const int g = item >> 8, t = (item >> 4) & 15, cp = item & 15, s = lane >> 2, c0 = (lane & 3) * 4; u32x2 w; w.x = 0u; w.y = 0u;
;     if (s <= t) { const f32x4 k = *(const f32x4*)((const float*)(P.ws + WS_KTAB) + ((size_t)(g * 16 + (t - s)) * 16 + cp) * 16 + c0); w.x = pk2(k[0], k[1]); w.y = pk2(k[2], k[3]); }
;     *((u32x2*)((bf16_t*)(P.ws + WS_TCAT) + (size_t)item * 384) + lane) = w;
; }
.LBB0_680:
	s_cmpk_gt_i32 s90, 0x1fff
	s_cbranch_scc1 .LBB0_685
	s_add_u32 s4, s92, 0x2100000
	s_addc_u32 s5, s93, 0
	s_lshl_b32 s2, s66, 7
	s_lshl_b32 s6, s97, 4
	s_add_i32 s2, s2, s6
	v_readlane_b32 s6, v255, 1
	v_readlane_b32 s7, v255, 2
	s_lshl_b32 s12, s6, 7
	s_mul_i32 s7, s90, 0x300
	s_mul_hi_i32 s6, s90, 0x300
	s_add_u32 s7, s92, s7
	s_addc_u32 s8, s93, s6
	s_add_u32 s6, s7, 0x1700000
	s_addc_u32 s7, s8, 0
	s_mul_hi_i32 s13, s94, 0x300
	s_mul_i32 s14, s94, 0x300
	s_mov_b32 s9, 0
	v_mov_b32_e32 v1, 0
	s_mov_b32 s15, s90
	v_mbcnt_lo_u32_b32 v16, -1, 0
	v_mbcnt_hi_u32_b32 v16, -1, v16
	s_nop 0
	v_ashrrev_i32_e32 v17, 2, v16
	v_lshlrev_b32_e32 v18, 4, v16
	v_and_b32_e32 v18, 48, v18
	v_mov_b32_e32 v19, 0
	v_lshlrev_b32_e32 v30, 3, v16
	v_mov_b32_e32 v31, 0
.Ltoe_blk:
	s_bfe_u32 s8, s15, 0x40004
	v_cmp_ge_i32_e32 vcc, s8, v17
	s_ashr_i32 s16, s15, 4
	s_and_b32 s16, s16, -16
	s_or_b32 s16, s16, s8
	v_cndmask_b32_e64 v64, 0, 1, vcc
	v_sub_u32_e32 v4, s16, v17
	v_ashrrev_i32_e32 v5, 31, v4
	v_lshlrev_b64 v[4:5], 10, v[4:5]
	v_lshl_add_u64 v[4:5], s[4:5], 0, v[4:5]
	s_and_b32 s8, s2, 0xf0
	s_lshl_b32 s8, s8, 2
	v_lshl_add_u64 v[4:5], v[4:5], 0, s[8:9]
	v_lshl_add_u64 v[4:5], v[4:5], 0, v[18:19]
	global_load_dwordx4 v[40:43], v[4:5], off
	v_lshl_add_u64 v[56:57], s[6:7], 0, v[30:31]
	s_add_i32 s15, s15, s94
	s_add_i32 s2, s2, s12
	s_add_u32 s6, s6, s14
	s_addc_u32 s7, s7, s13
	s_cmpk_gt_i32 s15, 0x1fff
	s_cbranch_scc1 .Ltoe_f1
	s_bfe_u32 s8, s15, 0x40004
	v_cmp_ge_i32_e32 vcc, s8, v17
	s_ashr_i32 s16, s15, 4
	s_and_b32 s16, s16, -16
	s_or_b32 s16, s16, s8
	v_cndmask_b32_e64 v65, 0, 1, vcc
	v_sub_u32_e32 v4, s16, v17
	v_ashrrev_i32_e32 v5, 31, v4
	v_lshlrev_b64 v[4:5], 10, v[4:5]
	v_lshl_add_u64 v[4:5], s[4:5], 0, v[4:5]
	s_and_b32 s8, s2, 0xf0
	s_lshl_b32 s8, s8, 2
	v_lshl_add_u64 v[4:5], v[4:5], 0, s[8:9]
	v_lshl_add_u64 v[4:5], v[4:5], 0, v[18:19]
	global_load_dwordx4 v[44:47], v[4:5], off
	v_lshl_add_u64 v[58:59], s[6:7], 0, v[30:31]
	s_add_i32 s15, s15, s94
	s_add_i32 s2, s2, s12
	s_add_u32 s6, s6, s14
	s_addc_u32 s7, s7, s13
	s_cmpk_gt_i32 s15, 0x1fff
	s_cbranch_scc1 .Ltoe_f2
	s_bfe_u32 s8, s15, 0x40004
	v_cmp_ge_i32_e32 vcc, s8, v17
	s_ashr_i32 s16, s15, 4
	s_and_b32 s16, s16, -16
	s_or_b32 s16, s16, s8
	v_cndmask_b32_e64 v66, 0, 1, vcc
	v_sub_u32_e32 v4, s16, v17
	v_ashrrev_i32_e32 v5, 31, v4
	v_lshlrev_b64 v[4:5], 10, v[4:5]
	v_lshl_add_u64 v[4:5], s[4:5], 0, v[4:5]
	s_and_b32 s8, s2, 0xf0
	s_lshl_b32 s8, s8, 2
	v_lshl_add_u64 v[4:5], v[4:5], 0, s[8:9]
	v_lshl_add_u64 v[4:5], v[4:5], 0, v[18:19]
	global_load_dwordx4 v[48:51], v[4:5], off
	v_lshl_add_u64 v[60:61], s[6:7], 0, v[30:31]
	s_add_i32 s15, s15, s94
	s_add_i32 s2, s2, s12
	s_add_u32 s6, s6, s14
	s_addc_u32 s7, s7, s13
	s_cmpk_gt_i32 s15, 0x1fff
	s_cbranch_scc1 .Ltoe_f3
	s_bfe_u32 s8, s15, 0x40004
	v_cmp_ge_i32_e32 vcc, s8, v17
	s_ashr_i32 s16, s15, 4
	s_and_b32 s16, s16, -16
	s_or_b32 s16, s16, s8
	v_cndmask_b32_e64 v67, 0, 1, vcc
	v_sub_u32_e32 v4, s16, v17
	v_ashrrev_i32_e32 v5, 31, v4
	v_lshlrev_b64 v[4:5], 10, v[4:5]
	v_lshl_add_u64 v[4:5], s[4:5], 0, v[4:5]
	s_and_b32 s8, s2, 0xf0
	s_lshl_b32 s8, s8, 2
	v_lshl_add_u64 v[4:5], v[4:5], 0, s[8:9]
	v_lshl_add_u64 v[4:5], v[4:5], 0, v[18:19]
	global_load_dwordx4 v[52:55], v[4:5], off
	v_lshl_add_u64 v[62:63], s[6:7], 0, v[30:31]
	s_add_i32 s15, s15, s94
	s_add_i32 s2, s2, s12
	s_add_u32 s6, s6, s14
	s_addc_u32 s7, s7, s13
	s_cmpk_gt_i32 s15, 0x1fff
	s_cselect_b32 s16, 1, 0
	s_waitcnt vmcnt(3)
	v_cvt_pk_bf16_f32 v40, v40, v41
	v_cvt_pk_bf16_f32 v41, v42, v43
	v_cmp_ne_u32_e32 vcc, 0, v64
	s_nop 1
	v_cndmask_b32_e32 v40, 0, v40, vcc
	v_cndmask_b32_e32 v41, 0, v41, vcc
	global_store_dwordx2 v[56:57], v[40:41], off
	s_waitcnt vmcnt(3)
	v_cvt_pk_bf16_f32 v44, v44, v45
	v_cvt_pk_bf16_f32 v45, v46, v47
	v_cmp_ne_u32_e32 vcc, 0, v65
	s_nop 1
	v_cndmask_b32_e32 v44, 0, v44, vcc
	v_cndmask_b32_e32 v45, 0, v45, vcc
	global_store_dwordx2 v[58:59], v[44:45], off
	s_waitcnt vmcnt(3)
	v_cvt_pk_bf16_f32 v48, v48, v49
	v_cvt_pk_bf16_f32 v49, v50, v51
	v_cmp_ne_u32_e32 vcc, 0, v66
	s_nop 1
	v_cndmask_b32_e32 v48, 0, v48, vcc
	v_cndmask_b32_e32 v49, 0, v49, vcc
	global_store_dwordx2 v[60:61], v[48:49], off
	s_waitcnt vmcnt(3)
	v_cvt_pk_bf16_f32 v52, v52, v53
	v_cvt_pk_bf16_f32 v53, v54, v55
	v_cmp_ne_u32_e32 vcc, 0, v67
	s_nop 1
	v_cndmask_b32_e32 v52, 0, v52, vcc
	v_cndmask_b32_e32 v53, 0, v53, vcc
	global_store_dwordx2 v[62:63], v[52:53], off
	s_cmp_eq_u32 s16, 1
	s_cbranch_scc0 .Ltoe_blk
	s_branch .LBB0_685
.Ltoe_f3:
	s_waitcnt vmcnt(2)
	v_cvt_pk_bf16_f32 v40, v40, v41
	v_cvt_pk_bf16_f32 v41, v42, v43
	v_cmp_ne_u32_e32 vcc, 0, v64
	s_nop 1
	v_cndmask_b32_e32 v40, 0, v40, vcc
	v_cndmask_b32_e32 v41, 0, v41, vcc
	global_store_dwordx2 v[56:57], v[40:41], off
	s_waitcnt vmcnt(2)
	v_cvt_pk_bf16_f32 v44, v44, v45
	v_cvt_pk_bf16_f32 v45, v46, v47
	v_cmp_ne_u32_e32 vcc, 0, v65
	s_nop 1
	v_cndmask_b32_e32 v44, 0, v44, vcc
	v_cndmask_b32_e32 v45, 0, v45, vcc
	global_store_dwordx2 v[58:59], v[44:45], off
	s_waitcnt vmcnt(2)
	v_cvt_pk_bf16_f32 v48, v48, v49
	v_cvt_pk_bf16_f32 v49, v50, v51
	v_cmp_ne_u32_e32 vcc, 0, v66
	s_nop 1
	v_cndmask_b32_e32 v48, 0, v48, vcc
	v_cndmask_b32_e32 v49, 0, v49, vcc
	global_store_dwordx2 v[60:61], v[48:49], off
	s_branch .LBB0_685
.Ltoe_f2:
	s_waitcnt vmcnt(1)
	v_cvt_pk_bf16_f32 v40, v40, v41
	v_cvt_pk_bf16_f32 v41, v42, v43
	v_cmp_ne_u32_e32 vcc, 0, v64
	s_nop 1
	v_cndmask_b32_e32 v40, 0, v40, vcc
	v_cndmask_b32_e32 v41, 0, v41, vcc
	global_store_dwordx2 v[56:57], v[40:41], off
	s_waitcnt vmcnt(1)
	v_cvt_pk_bf16_f32 v44, v44, v45
	v_cvt_pk_bf16_f32 v45, v46, v47
	v_cmp_ne_u32_e32 vcc, 0, v65
	s_nop 1
	v_cndmask_b32_e32 v44, 0, v44, vcc
	v_cndmask_b32_e32 v45, 0, v45, vcc
	global_store_dwordx2 v[58:59], v[44:45], off
	s_branch .LBB0_685
.Ltoe_f1:
	s_waitcnt vmcnt(0)
	v_cvt_pk_bf16_f32 v40, v40, v41
	v_cvt_pk_bf16_f32 v41, v42, v43
	v_cmp_ne_u32_e32 vcc, 0, v64
	s_nop 1
	v_cndmask_b32_e32 v40, 0, v40, vcc
	v_cndmask_b32_e32 v41, 0, v41, vcc
	global_store_dwordx2 v[56:57], v[40:41], off
